# v10 plus phase-12 residual epilogue: first 4 second-half residual loads hoisted to the epilogue top into free registers
# baseline (speedup 1.0000x reference)
.LBB0_1844:
	v_lshl_or_b32 v162, s26, 8, v182
	v_lshl_add_u32 v166, s24, 8, v180
	v_ashrrev_i32_e32 v163, 31, v162
	v_lshlrev_b64 v[194:195], 1, v[162:163]
	v_ashrrev_i32_e32 v167, 31, v166
	v_lshl_add_u64 v[164:165], s[6:7], 0, v[194:195]
	v_lshlrev_b64 v[196:197], 13, v[166:167]
	v_lshl_add_u64 v[124:125], v[164:165], 0, v[196:197]
	global_load_dwordx4 v[186:189], v[124:125], off
	global_load_dwordx4 v[190:193], v[124:125], off offset:256
	v_or_b32_e32 v176, 16, v166
	v_or_b32_e32 v172, 32, v166
	v_or_b32_e32 v168, 48, v166
	v_ashrrev_i32_e32 v177, 31, v176
	v_ashrrev_i32_e32 v173, 31, v172
	v_ashrrev_i32_e32 v169, 31, v168
	v_lshlrev_b64 v[178:179], 13, v[176:177]
	v_lshlrev_b64 v[174:175], 13, v[172:173]
	v_cvt_f32_i32_e32 v203, v105
	v_cvt_f32_i32_e32 v202, v104
	v_cvt_f32_i32_e32 v205, v107
	v_cvt_f32_i32_e32 v204, v106
	v_lshlrev_b64 v[170:171], 13, v[168:169]
	v_lshl_add_u64 v[104:105], v[164:165], 0, v[178:179]
	v_lshl_add_u64 v[106:107], v[164:165], 0, v[174:175]
	v_cvt_f32_i32_e32 v199, v117
	v_cvt_f32_i32_e32 v198, v116
	v_cvt_f32_i32_e32 v201, v119
	v_cvt_f32_i32_e32 v200, v118
	v_lshl_add_u64 v[206:207], v[164:165], 0, v[170:171]
	s_mov_b32 s96, 0x100000
	s_mov_b32 s97, 0
	v_lshl_add_u64 v[248:249], v[124:125], 0, s[96:97]
	v_lshl_add_u64 v[250:251], v[104:105], 0, s[96:97]
	global_load_dwordx4 v[140:143], v[104:105], off
	global_load_dwordx4 v[136:139], v[104:105], off offset:256
	global_load_dwordx4 v[132:135], v[106:107], off
	global_load_dwordx4 v[124:127], v[106:107], off offset:256
	global_load_dwordx4 v[116:119], v[206:207], off
	s_nop 0
	global_load_dwordx4 v[104:107], v[206:207], off offset:256
	global_load_dwordx4 v[232:235], v[248:249], off
	global_load_dwordx4 v[236:239], v[248:249], off offset:256
	global_load_dwordx4 v[240:243], v[250:251], off
	global_load_dwordx4 v[244:247], v[250:251], off offset:256
	v_cvt_f32_i32_e32 v129, v129
	v_cvt_f32_i32_e32 v128, v128
	v_cvt_f32_i32_e32 v131, v131
	v_cvt_f32_i32_e32 v130, v130
	v_cvt_f32_i32_e32 v121, v121
	v_cvt_f32_i32_e32 v120, v120
	v_cvt_f32_i32_e32 v123, v123
	v_cvt_f32_i32_e32 v122, v122
	s_waitcnt vmcnt(4)
	v_lshlrev_b32_e32 v206, 16, v186
	v_and_b32_e32 v207, 0xffff0000, v186
	v_lshlrev_b32_e32 v186, 16, v187
	v_and_b32_e32 v187, 0xffff0000, v187
	v_lshlrev_b32_e32 v208, 16, v188
	v_and_b32_e32 v209, 0xffff0000, v188
	v_lshlrev_b32_e32 v210, 16, v190
	v_and_b32_e32 v211, 0xffff0000, v190
	v_lshlrev_b32_e32 v190, 16, v191
	v_and_b32_e32 v191, 0xffff0000, v191
	v_lshlrev_b32_e32 v188, 16, v189
	v_and_b32_e32 v189, 0xffff0000, v189
	v_lshlrev_b32_e32 v212, 16, v192
	v_and_b32_e32 v213, 0xffff0000, v192
	v_pk_fma_f32 v[186:187], v[200:201], s[14:15], v[186:187] op_sel_hi:[1,0,1]
	v_pk_fma_f32 v[198:199], v[198:199], s[14:15], v[206:207] op_sel_hi:[1,0,1]
	v_pk_fma_f32 v[200:201], v[202:203], s[14:15], v[208:209] op_sel_hi:[1,0,1]
	v_pk_fma_f32 v[190:191], v[130:131], s[14:15], v[190:191] op_sel_hi:[1,0,1]
	v_pk_fma_f32 v[202:203], v[128:129], s[14:15], v[210:211] op_sel_hi:[1,0,1]
	v_lshlrev_b32_e32 v192, 16, v193
	v_and_b32_e32 v193, 0xffff0000, v193
	v_pk_fma_f32 v[188:189], v[204:205], s[14:15], v[188:189] op_sel_hi:[1,0,1]
	v_pk_fma_f32 v[204:205], v[120:121], s[14:15], v[212:213] op_sel_hi:[1,0,1]
	v_cvt_pk_bf16_f32 v128, v198, v199
	v_cvt_pk_bf16_f32 v129, v186, v187
	v_mul_f32_e32 v120, v199, v199
	v_mul_f32_e32 v121, v187, v187
	v_mul_f32_e32 v185, v203, v203
	v_mul_f32_e32 v187, v191, v191
	v_pk_fma_f32 v[192:193], v[122:123], s[14:15], v[192:193] op_sel_hi:[1,0,1]
	v_cvt_pk_bf16_f32 v130, v200, v201
	v_cvt_pk_bf16_f32 v131, v188, v189
	v_mul_f32_e32 v122, v201, v201
	v_mul_f32_e32 v123, v189, v189
	v_mul_f32_e32 v189, v205, v205
	v_fmac_f32_e32 v120, v198, v198
	v_fmac_f32_e32 v121, v186, v186
	v_fmac_f32_e32 v185, v202, v202
	v_fmac_f32_e32 v187, v190, v190
	v_mul_f32_e32 v199, v193, v193
	v_fmac_f32_e32 v122, v200, v200
	v_fmac_f32_e32 v189, v204, v204
	v_add_f32_e32 v120, v120, v121
	v_add_f32_e32 v121, v185, v187
	v_fmac_f32_e32 v123, v188, v188
	v_add_f32_e32 v120, v122, v120
	v_add_f32_e32 v121, v189, v121
	v_fmac_f32_e32 v199, v192, v192
	v_add_f32_e32 v120, v123, v120
	v_add_f32_e32 v121, v199, v121
	v_and_b32_e32 v122, 64, v184
	v_add_f32_e32 v121, v120, v121
	v_xor_b32_e32 v120, 16, v184
	v_add_u32_e32 v185, 64, v122
	v_cmp_lt_i32_e32 vcc, v120, v185
	v_lshl_add_u64 v[122:123], s[6:7], 0, v[196:197]
	v_lshl_add_u64 v[186:187], v[122:123], 0, v[194:195]
	v_cndmask_b32_e32 v120, v184, v120, vcc
	v_lshlrev_b32_e32 v120, 2, v120
	ds_bpermute_b32 v188, v120, v121
	global_store_dwordx4 v[186:187], v[128:131], off
	s_waitcnt lgkmcnt(0)
	v_add_f32_e32 v122, v121, v188
	v_xor_b32_e32 v121, 32, v184
	v_cmp_lt_i32_e32 vcc, v121, v185
	v_cvt_pk_bf16_f32 v128, v202, v203
	v_cvt_pk_bf16_f32 v129, v190, v191
	v_cvt_pk_bf16_f32 v130, v204, v205
	v_cvt_pk_bf16_f32 v131, v192, v193
	global_store_dwordx4 v[186:187], v[128:131], off offset:256
	s_nop 0
	v_cndmask_b32_e32 v121, v184, v121, vcc
	v_lshlrev_b32_e32 v121, 2, v121
	ds_bpermute_b32 v123, v121, v122
	s_and_saveexec_b64 s[24:25], s[2:3]
	s_cbranch_execz .LBB0_1846
	s_waitcnt lgkmcnt(0)
	v_add_f32_e32 v122, v122, v123
	v_fma_f32 v122, v122, s49, 0.5
	v_trunc_f32_e32 v122, v122
	v_mul_f32_e32 v123, 0x2f800000, v122
	v_floor_f32_e32 v123, v123
	v_fmac_f32_e32 v122, 0xcf800000, v123
	v_cvt_u32_f32_e32 v122, v122
	v_cvt_u32_f32_e32 v123, v123
	v_lshl_add_u64 v[128:129], v[166:167], 3, s[8:9]
	global_atomic_add_x2 v[128:129], v[122:123], off

.LBB0_1852:
	s_or_b64 exec, exec, s[24:25]
	v_add_u32_e32 v100, 0x80, v166
	v_ashrrev_i32_e32 v101, 31, v100
	v_lshlrev_b64 v[110:111], 13, v[100:101]
	s_waitcnt lgkmcnt(0)
	v_lshl_add_u64 v[64:65], v[164:165], 0, v[110:111]
	s_waitcnt vmcnt(8)
	v_mov_b32_e32 v102, v232
	v_mov_b32_e32 v103, v233
	v_mov_b32_e32 v104, v234
	v_mov_b32_e32 v105, v235
	v_mov_b32_e32 v106, v236
	v_mov_b32_e32 v107, v237
	v_mov_b32_e32 v108, v238
	v_mov_b32_e32 v109, v239
	v_add_u32_e32 v96, 0x90, v166
	v_add_u32_e32 v92, 0xa0, v166
	v_add_u32_e32 v88, 0xb0, v166
	v_ashrrev_i32_e32 v97, 31, v96
	v_ashrrev_i32_e32 v93, 31, v92
	v_ashrrev_i32_e32 v89, 31, v88
	v_lshlrev_b64 v[98:99], 13, v[96:97]
	v_lshlrev_b64 v[94:95], 13, v[92:93]
	v_lshlrev_b64 v[90:91], 13, v[88:89]
	v_lshl_add_u64 v[64:65], v[164:165], 0, v[98:99]
	v_lshl_add_u64 v[66:67], v[164:165], 0, v[94:95]
	v_lshl_add_u64 v[112:113], v[164:165], 0, v[90:91]
	v_mov_b32_e32 v84, v240
	v_mov_b32_e32 v85, v241
	v_mov_b32_e32 v86, v242
	v_mov_b32_e32 v87, v243
	v_mov_b32_e32 v80, v244
	v_mov_b32_e32 v81, v245
	v_mov_b32_e32 v82, v246
	v_mov_b32_e32 v83, v247
	global_load_dwordx4 v[76:79], v[66:67], off
	global_load_dwordx4 v[72:75], v[66:67], off offset:256
	global_load_dwordx4 v[68:71], v[112:113], off
	s_nop 0
	global_load_dwordx4 v[64:67], v[112:113], off offset:256
	v_cvt_f32_i32_e32 v61, v61
	v_cvt_f32_i32_e32 v60, v60
	v_cvt_f32_i32_e32 v63, v63
	v_cvt_f32_i32_e32 v62, v62
	v_cvt_f32_i32_e32 v53, v53
	v_cvt_f32_i32_e32 v52, v52
	v_cvt_f32_i32_e32 v55, v55
	v_cvt_f32_i32_e32 v54, v54
	v_cvt_f32_i32_e32 v57, v57
	v_cvt_f32_i32_e32 v56, v56
	v_cvt_f32_i32_e32 v59, v59
	v_cvt_f32_i32_e32 v58, v58
	v_cvt_f32_i32_e32 v49, v49
	v_cvt_f32_i32_e32 v48, v48
	v_cvt_f32_i32_e32 v51, v51
	v_cvt_f32_i32_e32 v50, v50
	s_waitcnt vmcnt(7)
	v_lshlrev_b32_e32 v112, 16, v102
	v_and_b32_e32 v113, 0xffff0000, v102
	v_lshlrev_b32_e32 v102, 16, v103
	v_and_b32_e32 v103, 0xffff0000, v103
	s_waitcnt vmcnt(6)
	v_lshlrev_b32_e32 v116, 16, v106
	v_and_b32_e32 v117, 0xffff0000, v106
	v_lshlrev_b32_e32 v106, 16, v107
	v_and_b32_e32 v107, 0xffff0000, v107
	v_lshlrev_b32_e32 v114, 16, v104
	v_and_b32_e32 v115, 0xffff0000, v104
	v_lshlrev_b32_e32 v104, 16, v105
	v_and_b32_e32 v105, 0xffff0000, v105
	v_lshlrev_b32_e32 v118, 16, v108
	v_and_b32_e32 v119, 0xffff0000, v108
	v_pk_fma_f32 v[62:63], v[62:63], s[14:15], v[102:103] op_sel_hi:[1,0,1]
	v_pk_fma_f32 v[60:61], v[60:61], s[14:15], v[112:113] op_sel_hi:[1,0,1]
	v_pk_fma_f32 v[54:55], v[54:55], s[14:15], v[106:107] op_sel_hi:[1,0,1]
	v_pk_fma_f32 v[52:53], v[52:53], s[14:15], v[116:117] op_sel_hi:[1,0,1]
	v_lshlrev_b32_e32 v108, 16, v109
	v_and_b32_e32 v109, 0xffff0000, v109
	v_pk_fma_f32 v[58:59], v[58:59], s[14:15], v[104:105] op_sel_hi:[1,0,1]
	v_pk_fma_f32 v[56:57], v[56:57], s[14:15], v[114:115] op_sel_hi:[1,0,1]
	v_pk_fma_f32 v[104:105], v[48:49], s[14:15], v[118:119] op_sel_hi:[1,0,1]
	v_cvt_pk_bf16_f32 v48, v60, v61
	v_cvt_pk_bf16_f32 v49, v62, v63
	v_mul_f32_e32 v61, v61, v61
	v_mul_f32_e32 v63, v63, v63
	v_mul_f32_e32 v106, v53, v53
	v_mul_f32_e32 v107, v55, v55
	v_pk_fma_f32 v[102:103], v[50:51], s[14:15], v[108:109] op_sel_hi:[1,0,1]
	v_cvt_pk_bf16_f32 v50, v56, v57
	v_cvt_pk_bf16_f32 v51, v58, v59
	v_mul_f32_e32 v57, v57, v57
	v_mul_f32_e32 v59, v59, v59
	v_mul_f32_e32 v108, v105, v105
	v_fmac_f32_e32 v61, v60, v60
	v_fmac_f32_e32 v63, v62, v62
	v_fmac_f32_e32 v106, v52, v52
	v_fmac_f32_e32 v107, v54, v54
	v_mul_f32_e32 v109, v103, v103
	v_fmac_f32_e32 v57, v56, v56
	v_fmac_f32_e32 v59, v58, v58
	v_fmac_f32_e32 v108, v104, v104
	v_add_f32_e32 v56, v61, v63
	v_add_f32_e32 v58, v106, v107
	v_fmac_f32_e32 v109, v102, v102
	v_add_f32_e32 v56, v57, v56
	v_add_f32_e32 v57, v108, v58
	v_add_f32_e32 v56, v59, v56
	v_add_f32_e32 v57, v109, v57
	v_add_f32_e32 v58, v56, v57
	ds_bpermute_b32 v59, v120, v58
	v_lshl_add_u64 v[56:57], s[6:7], 0, v[110:111]
	v_lshl_add_u64 v[56:57], v[162:163], 1, v[56:57]
	global_store_dwordx4 v[56:57], v[48:51], off
	s_waitcnt lgkmcnt(0)
	s_nop 0
	v_add_f32_e32 v48, v58, v59
	ds_bpermute_b32 v49, v121, v48
	v_cvt_pk_bf16_f32 v50, v52, v53
	v_cvt_pk_bf16_f32 v51, v54, v55
	v_cvt_pk_bf16_f32 v52, v104, v105
	v_cvt_pk_bf16_f32 v53, v102, v103
	global_store_dwordx4 v[56:57], v[50:53], off offset:256
	s_and_saveexec_b64 s[24:25], s[2:3]
	s_cbranch_execz .LBB0_1854
	s_waitcnt lgkmcnt(0)
	v_add_f32_e32 v48, v48, v49
	v_fma_f32 v48, v48, s49, 0.5
	v_trunc_f32_e32 v48, v48
	v_mul_f32_e32 v49, 0x2f800000, v48
	v_floor_f32_e32 v49, v49
	v_fmac_f32_e32 v48, 0xcf800000, v49
	v_cvt_u32_f32_e32 v48, v48
	v_cvt_u32_f32_e32 v49, v49
	v_lshl_add_u64 v[50:51], v[100:101], 3, s[8:9]
	global_atomic_add_x2 v[50:51], v[48:49], off
